# t1 + GQA A-step V-tile LDS writes moved from right after the barrier into the next scheduled region (behind its K reads)
# baseline (speedup 1.0000x reference)
.Lgqa_joinA:
	s_barrier
	v_cndmask_b32_e64 v217, v251, 1.0, s[6:7]
	v_cmp_gt_f32_e32 vcc, 1.0, v217
	s_cbranch_vccz .LBB0_743
	s_and_saveexec_b64 s[10:11], s[4:5]
	ds_write_b32 v194, v217 offset:128
	s_or_b64 exec, exec, s[10:11]
	s_waitcnt lgkmcnt(0)
	v_add_u32_e32 v163, v192, v144
	ds_read_b128 v[164:167], v163 offset:224
	ds_read_b128 v[168:171], v163 offset:192
	ds_read_b128 v[212:215], v163 offset:160
	ds_read_b128 v[218:221], v163 offset:128
	s_waitcnt lgkmcnt(3)
	v_pk_mul_f32 v[60:61], v[60:61], v[164:165]
	s_waitcnt lgkmcnt(2)
	v_pk_mul_f32 v[56:57], v[56:57], v[168:169]
	s_waitcnt lgkmcnt(1)
	v_pk_mul_f32 v[52:53], v[52:53], v[212:213]
	v_pk_mul_f32 v[62:63], v[62:63], v[166:167]
	v_pk_mul_f32 v[58:59], v[58:59], v[170:171]
	v_pk_mul_f32 v[54:55], v[54:55], v[214:215]
	s_waitcnt lgkmcnt(0)
	v_pk_mul_f32 v[50:51], v[50:51], v[220:221]
	v_pk_mul_f32 v[48:49], v[48:49], v[218:219]
	v_pk_mul_f32 v[44:45], v[44:45], v[164:165]
	v_pk_mul_f32 v[40:41], v[40:41], v[168:169]
	v_pk_mul_f32 v[36:37], v[36:37], v[212:213]
	v_pk_mul_f32 v[46:47], v[46:47], v[166:167]
	v_pk_mul_f32 v[42:43], v[42:43], v[170:171]
	v_pk_mul_f32 v[38:39], v[38:39], v[214:215]
	v_pk_mul_f32 v[34:35], v[34:35], v[220:221]
	v_pk_mul_f32 v[32:33], v[32:33], v[218:219]
	v_pk_mul_f32 v[28:29], v[28:29], v[164:165]
	v_pk_mul_f32 v[24:25], v[24:25], v[168:169]
	v_pk_mul_f32 v[20:21], v[20:21], v[212:213]
	v_pk_mul_f32 v[30:31], v[30:31], v[166:167]
	v_pk_mul_f32 v[26:27], v[26:27], v[170:171]
	v_pk_mul_f32 v[22:23], v[22:23], v[214:215]
	v_pk_mul_f32 v[18:19], v[18:19], v[220:221]
	v_pk_mul_f32 v[16:17], v[16:17], v[218:219]
	v_pk_mul_f32 v[12:13], v[12:13], v[164:165]
	v_pk_mul_f32 v[8:9], v[8:9], v[168:169]
	v_pk_mul_f32 v[4:5], v[4:5], v[212:213]
	v_pk_mul_f32 v[14:15], v[14:15], v[166:167]
	v_pk_mul_f32 v[10:11], v[10:11], v[170:171]
	v_pk_mul_f32 v[6:7], v[6:7], v[214:215]
	v_pk_mul_f32 v[2:3], v[2:3], v[220:221]
	v_pk_mul_f32 v[0:1], v[0:1], v[218:219]
.LBB0_743:
	v_cndmask_b32_e64 v216, v250, v174, s[6:7]
	v_mul_f32_e32 v212, 0xbe0293ee, v216
	v_fmamk_f32 v162, v80, 0x3e0293ee, v212
	v_fmamk_f32 v177, v81, 0x3e0293ee, v212
	v_fmamk_f32 v163, v82, 0x3e0293ee, v212
	v_fmamk_f32 v176, v83, 0x3e0293ee, v212
	v_fmamk_f32 v164, v84, 0x3e0293ee, v212
	v_fmamk_f32 v175, v85, 0x3e0293ee, v212
	v_fmamk_f32 v165, v86, 0x3e0293ee, v212
	v_fmamk_f32 v174, v87, 0x3e0293ee, v212
	v_fmamk_f32 v166, v88, 0x3e0293ee, v212
	v_fmamk_f32 v173, v89, 0x3e0293ee, v212
	v_fmamk_f32 v167, v90, 0x3e0293ee, v212
	v_fmamk_f32 v172, v91, 0x3e0293ee, v212
	v_fmamk_f32 v168, v92, 0x3e0293ee, v212
	v_fmamk_f32 v171, v93, 0x3e0293ee, v212
	v_fmamk_f32 v169, v94, 0x3e0293ee, v212
	v_fmamk_f32 v170, v95, 0x3e0293ee, v212
	ds_read_b128 v[240:243], v200 offset:32768
	ds_read_b128 v[244:247], v208 offset:32768
	ds_read_b128 v[248:251], v207 offset:32768
	s_waitcnt lgkmcnt(2)
	v_mfma_f32_32x32x16_bf16 v[80:95], v[240:243], v[124:127], 0
	ds_read_b128 v[240:243], v206 offset:32768
	v_exp_f32_e32 v162, v162
	v_exp_f32_e32 v177, v177
	v_fmamk_f32 v219, v70, 0x3e0293ee, v212
	s_waitcnt lgkmcnt(2)
	v_mfma_f32_32x32x16_bf16 v[80:95], v[244:247], v[120:123], v[80:95]
	ds_read_b128 v[244:247], v205 offset:32768
	v_exp_f32_e32 v163, v163
	v_exp_f32_e32 v176, v176
	v_fmamk_f32 v220, v71, 0x3e0293ee, v212
	s_waitcnt lgkmcnt(2)
	v_mfma_f32_32x32x16_bf16 v[80:95], v[248:251], v[116:119], v[80:95]
	ds_read_b128 v[248:251], v204 offset:32768
	v_exp_f32_e32 v164, v164
	v_exp_f32_e32 v175, v175
	v_fmamk_f32 v225, v64, 0x3e0293ee, v212
	s_waitcnt lgkmcnt(2)
	v_mfma_f32_32x32x16_bf16 v[80:95], v[240:243], v[112:115], v[80:95]
	ds_read_b128 v[240:243], v202 offset:32768
	v_exp_f32_e32 v165, v165
	v_exp_f32_e32 v174, v174
	v_fmamk_f32 v226, v65, 0x3e0293ee, v212
	s_waitcnt lgkmcnt(2)
	v_mfma_f32_32x32x16_bf16 v[80:95], v[244:247], v[108:111], v[80:95]
	ds_read_b128 v[244:247], v201 offset:32768
	v_exp_f32_e32 v166, v166
	v_exp_f32_e32 v173, v173
	v_fmamk_f32 v227, v66, 0x3e0293ee, v212
	s_waitcnt lgkmcnt(2)
	v_mfma_f32_32x32x16_bf16 v[80:95], v[248:251], v[104:107], v[80:95]
	ds_read_b128 v[248:251], v200 offset:40960
	v_exp_f32_e32 v167, v167
	v_exp_f32_e32 v172, v172
	v_fmamk_f32 v232, v67, 0x3e0293ee, v212
	s_waitcnt lgkmcnt(2)
	v_mfma_f32_32x32x16_bf16 v[80:95], v[240:243], v[100:103], v[80:95]
	ds_read_b128 v[240:243], v208 offset:40960
	v_exp_f32_e32 v168, v168
	v_exp_f32_e32 v171, v171
	v_fmamk_f32 v233, v68, 0x3e0293ee, v212
	s_waitcnt lgkmcnt(2)
	v_mfma_f32_32x32x16_bf16 v[80:95], v[244:247], v[96:99], v[80:95]
	ds_read_b128 v[244:247], v207 offset:40960
	v_exp_f32_e32 v169, v169
	v_exp_f32_e32 v170, v170
	v_fmamk_f32 v218, v69, 0x3e0293ee, v212
	v_fmamk_f32 v221, v72, 0x3e0293ee, v212
	v_fmamk_f32 v222, v73, 0x3e0293ee, v212
	v_fmamk_f32 v223, v74, 0x3e0293ee, v212
	v_fmamk_f32 v224, v75, 0x3e0293ee, v212
	v_fmamk_f32 v213, v76, 0x3e0293ee, v212
	v_fmamk_f32 v234, v77, 0x3e0293ee, v212
	v_fmamk_f32 v235, v78, 0x3e0293ee, v212
	v_fmac_f32_e32 v212, 0x3e0293ee, v79
	s_waitcnt lgkmcnt(2)
	v_mfma_f32_32x32x16_bf16 v[64:79], v[248:251], v[124:127], 0
	ds_read_b128 v[248:251], v206 offset:40960
	v_exp_f32_e32 v215, v226
	v_exp_f32_e32 v226, v232
	s_waitcnt lgkmcnt(2)
	v_mfma_f32_32x32x16_bf16 v[64:79], v[240:243], v[120:123], v[64:79]
	ds_read_b128 v[240:243], v205 offset:40960
	v_exp_f32_e32 v232, v219
	v_add_f32_e32 v219, 0, v162
	v_add_f32_e32 v219, v177, v219
	v_add_f32_e32 v219, v163, v219
	s_waitcnt lgkmcnt(2)
	v_mfma_f32_32x32x16_bf16 v[64:79], v[244:247], v[116:119], v[64:79]
	ds_read_b128 v[244:247], v204 offset:40960
	v_add_f32_e32 v219, v176, v219
	v_add_f32_e32 v219, v164, v219
	v_add_f32_e32 v219, v175, v219
	v_add_f32_e32 v219, v165, v219
	v_add_f32_e32 v219, v174, v219
	s_waitcnt lgkmcnt(2)
	v_mfma_f32_32x32x16_bf16 v[64:79], v[248:251], v[112:115], v[64:79]
	ds_read_b128 v[248:251], v202 offset:40960
	v_add_f32_e32 v219, v166, v219
	v_add_f32_e32 v219, v173, v219
	v_add_f32_e32 v219, v167, v219
	v_add_f32_e32 v219, v172, v219
	v_add_f32_e32 v219, v168, v219
	s_waitcnt lgkmcnt(2)
	v_mfma_f32_32x32x16_bf16 v[64:79], v[240:243], v[108:111], v[64:79]
	ds_read_b128 v[240:243], v201 offset:40960
	v_exp_f32_e32 v214, v225
	v_add_f32_e32 v219, v171, v219
	v_exp_f32_e32 v225, v227
	s_waitcnt lgkmcnt(2)
	v_mfma_f32_32x32x16_bf16 v[64:79], v[244:247], v[104:107], v[64:79]
	v_add_f32_e32 v219, v169, v219
	v_add_f32_e32 v219, v170, v219
	v_exp_f32_e32 v227, v233
	v_add_f32_e32 v219, v214, v219
	s_waitcnt lgkmcnt(1)
	v_mfma_f32_32x32x16_bf16 v[64:79], v[248:251], v[100:103], v[64:79]
	v_exp_f32_e32 v218, v218
	v_add_f32_e32 v219, v215, v219
	v_add_f32_e32 v219, v225, v219
	v_add_f32_e32 v219, v226, v219
	s_waitcnt lgkmcnt(0)
	v_mfma_f32_32x32x16_bf16 v[64:79], v[240:243], v[96:99], v[64:79]
	v_exp_f32_e32 v233, v220
	v_exp_f32_e32 v221, v221
	v_add_f32_e32 v219, v227, v219
	s_cmp_ge_u32 s14, s91
	s_cselect_b64 s[10:11], -1, 0
	s_waitcnt vmcnt(0)
	ds_write_b128 v198, v[154:157] offset:49152
	ds_write_b128 v199, v[158:161] offset:49152
	ds_write_b128 v195, v[128:131]
	ds_write_b128 v196, v[132:135]
	s_ashr_i32 s9, s8, 31
	s_mul_hi_u32 s100, s8, s40
	s_mul_i32 s101, s8, s41
	s_add_u32 s100, s100, s101
	s_mul_i32 s101, s9, s40
	s_add_u32 s100, s100, s101
	s_mul_i32 s6, s8, s40
	s_mov_b32 s7, s100
	s_lshl_b64 s[6:7], s[6:7], 1
	v_exp_f32_e32 v222, v222
	v_add_f32_e32 v219, v218, v219
	v_exp_f32_e32 v223, v223
	v_add_f32_e32 v219, v232, v219
	v_exp_f32_e32 v224, v224
	v_add_f32_e32 v219, v233, v219
	v_exp_f32_e32 v213, v213
	v_add_f32_e32 v219, v221, v219
	v_exp_f32_e32 v234, v234
	v_add_f32_e32 v219, v222, v219
	v_exp_f32_e32 v235, v235
	v_add_f32_e32 v219, v223, v219
	v_exp_f32_e32 v212, v212
	v_add_f32_e32 v219, v224, v219
	v_add_f32_e32 v219, v213, v219
	v_add_f32_e32 v219, v234, v219
	v_add_f32_e32 v219, v235, v219
	v_add_f32_e32 v219, v212, v219
	v_cvt_pk_bf16_f32 v162, v162, v177
	v_cvt_pk_bf16_f32 v163, v163, v176
	v_cvt_pk_bf16_f32 v164, v164, v175
	v_cvt_pk_bf16_f32 v165, v165, v174
	v_cvt_pk_bf16_f32 v169, v169, v170
	v_cvt_pk_bf16_f32 v170, v214, v215
	v_cvt_pk_bf16_f32 v176, v213, v234
	v_cvt_pk_bf16_f32 v177, v235, v212
	v_permlane32_swap_b32_e32 v162, v164
	v_permlane32_swap_b32_e32 v163, v165
	ds_read_b64_tr_b16 v[212:213], v197 offset:0
	ds_read_b64_tr_b16 v[214:215], v197 offset:0x800
	s_waitcnt lgkmcnt(0)
	v_mfma_f32_32x32x16_bf16 v[48:63], v[162:165], v[212:215], v[48:63]
	v_mov_b32_e32 v220, v219
	s_nop 1
	v_permlane32_swap_b32_e32 v219, v220
	v_cvt_pk_bf16_f32 v166, v166, v173
	v_cvt_pk_bf16_f32 v167, v167, v172
	v_cvt_pk_bf16_f32 v168, v168, v171
	v_cvt_pk_bf16_f32 v171, v225, v226
	v_cvt_pk_bf16_f32 v174, v221, v222
	v_cvt_pk_bf16_f32 v175, v223, v224
	v_permlane32_swap_b32_e32 v166, v168
	v_permlane32_swap_b32_e32 v167, v169
	ds_read_b64_tr_b16 v[222:223], v197 offset:0x1000
	ds_read_b64_tr_b16 v[224:225], v197 offset:0x1800
	s_waitcnt lgkmcnt(0)
	v_mfma_f32_32x32x16_bf16 v[48:63], v[166:169], v[222:225], v[48:63]
	v_cvt_pk_bf16_f32 v172, v227, v218
	v_cvt_pk_bf16_f32 v173, v232, v233
	s_nop 0
	v_permlane32_swap_b32_e32 v170, v172
	v_permlane32_swap_b32_e32 v171, v173
	v_permlane32_swap_b32_e32 v174, v176
	ds_read_b64_tr_b16 v[232:233], v197 offset:0x2000
	ds_read_b64_tr_b16 v[234:235], v197 offset:0x2800
	ds_read_b64_tr_b16 v[236:237], v197 offset:0x3000
	ds_read_b64_tr_b16 v[238:239], v197 offset:0x3800
	ds_read_b64_tr_b16 v[212:213], v197 offset:0x200
	ds_read_b64_tr_b16 v[214:215], v197 offset:0xa00
	ds_read_b64_tr_b16 v[222:223], v197 offset:0x1200
	ds_read_b64_tr_b16 v[224:225], v197 offset:0x1a00
	s_waitcnt lgkmcnt(6)
	v_mfma_f32_32x32x16_bf16 v[48:63], v[170:173], v[232:235], v[48:63]
	ds_read_b64_tr_b16 v[232:233], v197 offset:0x2200
	ds_read_b64_tr_b16 v[234:235], v197 offset:0x2a00
	v_permlane32_swap_b32_e32 v175, v177
	v_lshl_add_u64 v[128:129], s[6:7], 0, v[178:179]
	v_lshl_add_u64 v[132:133], s[6:7], 0, v[180:181]
	v_lshl_add_u64 v[136:137], s[6:7], 0, v[182:183]
	v_lshl_add_u64 v[140:141], s[6:7], 0, v[184:185]
	s_waitcnt lgkmcnt(6)
	v_mfma_f32_32x32x16_bf16 v[48:63], v[174:177], v[236:239], v[48:63]
	ds_read_b64_tr_b16 v[236:237], v197 offset:0x3200
	ds_read_b64_tr_b16 v[238:239], v197 offset:0x3a00
	v_max_f32_e32 v250, v81, v81
	v_max_f32_e32 v251, v80, v80
	v_max_f32_e32 v250, v251, v250
	v_max3_f32 v250, v250, v82, v83
	v_max3_f32 v250, v250, v84, v85
	s_waitcnt lgkmcnt(6)
	v_mfma_f32_32x32x16_bf16 v[32:47], v[162:165], v[212:215], v[32:47]
	ds_read_b64_tr_b16 v[212:213], v197 offset:0x400
	ds_read_b64_tr_b16 v[214:215], v197 offset:0xc00
	v_max3_f32 v250, v250, v86, v87
	v_max3_f32 v250, v250, v88, v89
	v_max3_f32 v250, v250, v90, v91
	v_max3_f32 v250, v250, v92, v93
	v_max3_f32 v250, v250, v94, v95
	s_waitcnt lgkmcnt(6)
	v_mfma_f32_32x32x16_bf16 v[32:47], v[166:169], v[222:225], v[32:47]
	ds_read_b64_tr_b16 v[222:223], v197 offset:0x1400
	ds_read_b64_tr_b16 v[224:225], v197 offset:0x1c00
	v_max3_f32 v250, v250, v64, v65
	v_max3_f32 v250, v250, v66, v67
	v_max3_f32 v250, v250, v68, v69
	v_max3_f32 v250, v250, v70, v71
	v_max3_f32 v250, v250, v72, v73
	global_load_dwordx4 v[128:131], v[128:129], off
	global_load_dwordx4 v[132:135], v[132:133], off
	global_load_dwordx4 v[136:139], v[136:137], off
	global_load_dwordx4 v[140:143], v[140:141], off
	s_waitcnt lgkmcnt(6)
	v_mfma_f32_32x32x16_bf16 v[32:47], v[170:173], v[232:235], v[32:47]
	ds_read_b64_tr_b16 v[232:233], v197 offset:0x2400
	ds_read_b64_tr_b16 v[234:235], v197 offset:0x2c00
	v_max3_f32 v250, v250, v74, v75
	v_max3_f32 v250, v250, v76, v77
	v_max3_f32 v250, v250, v78, v79
	v_mov_b32_e32 v251, v250
	s_nop 1
	v_permlane32_swap_b32_e32 v250, v251
	s_waitcnt lgkmcnt(6)
	v_mfma_f32_32x32x16_bf16 v[32:47], v[174:177], v[236:239], v[32:47]
	ds_read_b64_tr_b16 v[236:237], v197 offset:0x3400
	ds_read_b64_tr_b16 v[238:239], v197 offset:0x3c00
	v_max_f32_e32 v251, v251, v251
	v_max_f32_e32 v250, v250, v250
	v_max_f32_e32 v250, v250, v251
	v_sub_f32_e32 v251, v250, v216
	v_cmp_ge_f32_e32 vcc, s93, v251
	s_waitcnt lgkmcnt(6)
	v_mfma_f32_32x32x16_bf16 v[16:31], v[162:165], v[212:215], v[16:31]
	ds_read_b64_tr_b16 v[212:213], v197 offset:0x600
	ds_read_b64_tr_b16 v[214:215], v197 offset:0xe00
	v_max_f32_e32 v251, v216, v216
	v_max_f32_e32 v250, v251, v250
	v_sub_f32_e32 v251, v216, v250
	v_mul_f32_e32 v251, 0x3e0293ee, v251
	s_waitcnt lgkmcnt(6)
	v_mfma_f32_32x32x16_bf16 v[16:31], v[166:169], v[222:225], v[16:31]
	ds_read_b64_tr_b16 v[222:223], v197 offset:0x1600
	ds_read_b64_tr_b16 v[224:225], v197 offset:0x1e00
	v_exp_f32_e32 v251, v251
	s_waitcnt lgkmcnt(6)
	v_mfma_f32_32x32x16_bf16 v[16:31], v[170:173], v[232:235], v[16:31]
	ds_read_b64_tr_b16 v[232:233], v197 offset:0x2600
	ds_read_b64_tr_b16 v[234:235], v197 offset:0x2e00
	s_waitcnt lgkmcnt(6)
	v_mfma_f32_32x32x16_bf16 v[16:31], v[174:177], v[236:239], v[16:31]
	ds_read_b64_tr_b16 v[236:237], v197 offset:0x3600
	ds_read_b64_tr_b16 v[238:239], v197 offset:0x3e00
	s_waitcnt lgkmcnt(6)
	v_mfma_f32_32x32x16_bf16 v[0:15], v[162:165], v[212:215], v[0:15]
	s_waitcnt lgkmcnt(4)
	v_mfma_f32_32x32x16_bf16 v[0:15], v[166:169], v[222:225], v[0:15]
	s_waitcnt lgkmcnt(2)
	v_mfma_f32_32x32x16_bf16 v[0:15], v[170:173], v[232:235], v[0:15]
	s_waitcnt lgkmcnt(0)
	v_mfma_f32_32x32x16_bf16 v[0:15], v[174:177], v[236:239], v[0:15]
	s_cmp_eq_u64 vcc, exec
	s_cselect_b64 s[6:7], -1, 0
	s_barrier
	v_cndmask_b32_e64 v218, v251, 1.0, s[6:7]
	v_cmp_gt_f32_e32 vcc, 1.0, v218
	ds_write_b128 v195, v[146:149] offset:16384
	ds_write_b128 v196, v[150:153] offset:16384
	s_cbranch_vccz .LBB0_749
	s_and_saveexec_b64 s[12:13], s[4:5]
	ds_write_b32 v194, v218 offset:128
	s_or_b64 exec, exec, s[12:13]
	s_waitcnt lgkmcnt(0)
	v_add_u32_e32 v158, v192, v144
	ds_read_b128 v[146:149], v158 offset:224
	ds_read_b128 v[150:153], v158 offset:192
	ds_read_b128 v[154:157], v158 offset:160
	ds_read_b128 v[158:161], v158 offset:128
	s_waitcnt lgkmcnt(3)
	v_pk_mul_f32 v[60:61], v[60:61], v[146:147]
	s_waitcnt lgkmcnt(2)
	v_pk_mul_f32 v[56:57], v[56:57], v[150:151]
	s_waitcnt lgkmcnt(1)
	v_pk_mul_f32 v[52:53], v[52:53], v[154:155]
	v_pk_mul_f32 v[62:63], v[62:63], v[148:149]
	v_pk_mul_f32 v[58:59], v[58:59], v[152:153]
	v_pk_mul_f32 v[54:55], v[54:55], v[156:157]
	s_waitcnt lgkmcnt(0)
	v_pk_mul_f32 v[50:51], v[50:51], v[160:161]
	v_pk_mul_f32 v[48:49], v[48:49], v[158:159]
	v_pk_mul_f32 v[44:45], v[44:45], v[146:147]
	v_pk_mul_f32 v[40:41], v[40:41], v[150:151]
	v_pk_mul_f32 v[36:37], v[36:37], v[154:155]
	v_pk_mul_f32 v[46:47], v[46:47], v[148:149]
	v_pk_mul_f32 v[42:43], v[42:43], v[152:153]
	v_pk_mul_f32 v[38:39], v[38:39], v[156:157]
	v_pk_mul_f32 v[34:35], v[34:35], v[160:161]
	v_pk_mul_f32 v[32:33], v[32:33], v[158:159]
	v_pk_mul_f32 v[28:29], v[28:29], v[146:147]
	v_pk_mul_f32 v[24:25], v[24:25], v[150:151]
	v_pk_mul_f32 v[20:21], v[20:21], v[154:155]
	v_pk_mul_f32 v[30:31], v[30:31], v[148:149]
	v_pk_mul_f32 v[26:27], v[26:27], v[152:153]
	v_pk_mul_f32 v[22:23], v[22:23], v[156:157]
	v_pk_mul_f32 v[18:19], v[18:19], v[160:161]
	v_pk_mul_f32 v[16:17], v[16:17], v[158:159]
	v_pk_mul_f32 v[12:13], v[12:13], v[146:147]
	v_pk_mul_f32 v[8:9], v[8:9], v[150:151]
	v_pk_mul_f32 v[4:5], v[4:5], v[154:155]
	v_pk_mul_f32 v[14:15], v[14:15], v[148:149]
	v_pk_mul_f32 v[10:11], v[10:11], v[152:153]
	v_pk_mul_f32 v[6:7], v[6:7], v[156:157]
	v_pk_mul_f32 v[2:3], v[2:3], v[160:161]
	v_pk_mul_f32 v[0:1], v[0:1], v[158:159]
